# EpiFinal row-sum exchange: drop the L2 writeback+invalidate around the panel counter (partials are sc1 write-through stores/loads within one XCD)
# speedup vs baseline: 1.0095x; 1.0048x over previous
.LBB0_1189:
	s_or_b64 exec, exec, s[26:27]
	s_waitcnt vmcnt(0)
	s_barrier
	s_and_saveexec_b64 s[24:25], s[6:7]
	s_cbranch_execz .LBB0_1201
	s_lshl_b32 s26, s22, 2
	s_mov_b64 s[28:29], exec
	s_ashr_i32 s27, s26, 31
	s_lshl_b64 s[26:27], s[26:27], 2
	v_mbcnt_lo_u32_b32 v0, s28, 0
	s_add_u32 s26, s45, s26
	v_mbcnt_hi_u32_b32 v0, s29, v0
	s_addc_u32 s27, s46, s27
	v_cmp_eq_u32_e32 vcc, 0, v0
	s_waitcnt vmcnt(0) lgkmcnt(0)
	s_and_saveexec_b64 s[30:31], vcc
	s_cbranch_execz .LBB0_1192
	s_bcnt1_i32_b64 s23, s[28:29]
	v_mov_b32_e32 v0, s23
	global_atomic_add v147, v0, s[26:27]

.LBB0_1194:
	global_load_dword v0, v147, s[26:27] sc1
	s_mov_b64 s[28:29], -1
	s_waitcnt vmcnt(0)
	v_cmp_lt_u32_e32 vcc, 3, v0
	s_cbranch_vccnz .LBB0_1193
	s_sleep 1
	global_load_dword v0, v147, s[26:27] sc1
	s_waitcnt vmcnt(0)
	v_cmp_gt_u32_e32 vcc, 4, v0
	s_cbranch_vccz .LBB0_1193
	s_sleep 1
	global_load_dword v0, v147, s[26:27] sc1
	s_waitcnt vmcnt(0)
	v_cmp_gt_u32_e32 vcc, 4, v0
	s_cbranch_vccz .LBB0_1193
	s_sleep 1
	global_load_dword v0, v147, s[26:27] sc1
	s_waitcnt vmcnt(0)
	v_cmp_gt_u32_e32 vcc, 4, v0
	s_cbranch_vccz .LBB0_1193
	s_sleep 1
	global_load_dword v0, v147, s[26:27] sc1
	s_waitcnt vmcnt(0)
	v_cmp_gt_u32_e32 vcc, 4, v0
	s_cbranch_vccz .LBB0_1193
	s_add_i32 s23, s23, -5
	s_cmp_eq_u32 s23, 0
	s_cselect_b64 s[28:29], -1, 0
	s_sleep 1
	s_branch .LBB0_1193
.LBB0_1200:
	s_waitcnt vmcnt(0)
.LBB0_1201:
	s_or_b64 exec, exec, s[24:25]
	s_barrier
	s_and_saveexec_b64 s[24:25], s[4:5]
	s_cbranch_execz .LBB0_1203
	s_ashr_i32 s23, s22, 31
	s_lshl_b64 s[22:23], s[22:23], 12
	s_waitcnt lgkmcnt(0)
	v_lshl_add_u64 v[0:1], v[152:153], 0, s[22:23]
	global_load_dword v2, v[0:1], off sc1
	global_load_dword v3, v[0:1], off offset:4 sc1
	global_load_dword v4, v[0:1], off offset:8 sc1
	s_nop 0
	global_load_dword v0, v[0:1], off offset:12 sc1
	s_waitcnt vmcnt(3)
	v_add_f32_e32 v1, 0, v2
	s_waitcnt vmcnt(2)
	v_add_f32_e32 v1, v1, v3
	s_waitcnt vmcnt(1)
	v_add_f32_e32 v1, v1, v4
	s_waitcnt vmcnt(0)
	v_add_f32_e32 v0, v1, v0
	v_fmamk_f32 v0, v0, 0x3a800000, v213
	v_rsq_f32_e32 v0, v0
	ds_write_b32 v214, v0 offset:4096
